# v20 + final RMSNorm loop rewritten: gain vector loaded once, whole row in flight, next row prefetched into a second register set
# baseline (speedup 1.0000x reference)
; __global__ void __launch_bounds__(512, 2) fwd_kernel(Args args) {
;     ...
;         for (int m = gw; m < S; m += NGW) {
;             const float rs = rsqrtf(ssq_fin[m] * (1.0f / 1024.0f) + 1e-6f);
;             f32x4* xr = (f32x4*)(out + (size_t)m * D) + lane;
; #pragma unroll
;             for (int j = 0; j < 4; ++j) { const f32x4 gg = ((const f32x4*)gf + lane)[64 * j]; xr[64 * j] = xr[64 * j] * rs * gg; }
;         }
.LBB0_2571:
	global_load_dwordx4 v[20:23], v[2:3], off
	global_load_dwordx4 v[24:27], v[2:3], off offset:1024
	global_load_dwordx4 v[28:31], v[2:3], off offset:2048
	global_load_dwordx4 v[32:35], v[2:3], off offset:3072
	global_load_dword v18, v1, s[0:1]
	global_load_dwordx4 v[36:39], v[4:5], off offset:-2048
	global_load_dwordx4 v[40:43], v[4:5], off offset:-1024
	global_load_dwordx4 v[44:47], v[4:5], off
	global_load_dwordx4 v[48:51], v[4:5], off offset:1024
.Lrn_loop:
	s_add_i32 s2, s2, s16
	s_add_u32 s0, s0, s4
	s_addc_u32 s1, s1, s5
	v_lshl_add_u64 v[70:71], v[4:5], 0, s[6:7]
	s_cmpk_gt_i32 s2, 0x3fff
	s_cbranch_scc1 .Lrn_lastA
	global_load_dword v68, v1, s[0:1]
	global_load_dwordx4 v[52:55], v[70:71], off offset:-2048
	global_load_dwordx4 v[56:59], v[70:71], off offset:-1024
	global_load_dwordx4 v[60:63], v[70:71], off
	global_load_dwordx4 v[64:67], v[70:71], off offset:1024
	s_waitcnt vmcnt(5)
	v_fmamk_f32 v18, v18, 0x3a800000, v0
	v_mul_f32_e32 v19, 0x4b800000, v18
	v_cmp_gt_f32_e32 vcc, s3, v18
	s_nop 1
	v_cndmask_b32_e32 v18, v18, v19, vcc
	v_rsq_f32_e32 v18, v18
	s_nop 0
	v_mul_f32_e32 v19, 0x45800000, v18
	v_cndmask_b32_e32 v18, v18, v19, vcc
	v_pk_mul_f32 v[36:37], v[18:19], v[36:37] op_sel_hi:[0,1]
	v_pk_mul_f32 v[38:39], v[18:19], v[38:39] op_sel_hi:[0,1]
	v_pk_mul_f32 v[36:37], v[20:21], v[36:37]
	v_pk_mul_f32 v[38:39], v[22:23], v[38:39]
	global_store_dwordx4 v[4:5], v[36:39], off offset:-2048
	v_pk_mul_f32 v[40:41], v[18:19], v[40:41] op_sel_hi:[0,1]
	v_pk_mul_f32 v[42:43], v[18:19], v[42:43] op_sel_hi:[0,1]
	v_pk_mul_f32 v[40:41], v[24:25], v[40:41]
	v_pk_mul_f32 v[42:43], v[26:27], v[42:43]
	global_store_dwordx4 v[4:5], v[40:43], off offset:-1024
	v_pk_mul_f32 v[44:45], v[18:19], v[44:45] op_sel_hi:[0,1]
	v_pk_mul_f32 v[46:47], v[18:19], v[46:47] op_sel_hi:[0,1]
	v_pk_mul_f32 v[44:45], v[28:29], v[44:45]
	v_pk_mul_f32 v[46:47], v[30:31], v[46:47]
	global_store_dwordx4 v[4:5], v[44:47], off
	v_pk_mul_f32 v[48:49], v[18:19], v[48:49] op_sel_hi:[0,1]
	v_pk_mul_f32 v[50:51], v[18:19], v[50:51] op_sel_hi:[0,1]
	v_pk_mul_f32 v[48:49], v[32:33], v[48:49]
	v_pk_mul_f32 v[50:51], v[34:35], v[50:51]
	global_store_dwordx4 v[4:5], v[48:51], off offset:1024
	s_add_i32 s2, s2, s16
	s_add_u32 s0, s0, s4
	s_addc_u32 s1, s1, s5
	v_lshl_add_u64 v[4:5], v[70:71], 0, s[6:7]
	s_cmpk_gt_i32 s2, 0x3fff
	s_cbranch_scc1 .Lrn_lastB
	global_load_dword v18, v1, s[0:1]
	global_load_dwordx4 v[36:39], v[4:5], off offset:-2048
	global_load_dwordx4 v[40:43], v[4:5], off offset:-1024
	global_load_dwordx4 v[44:47], v[4:5], off
	global_load_dwordx4 v[48:51], v[4:5], off offset:1024
	s_waitcnt vmcnt(5)
	v_fmamk_f32 v68, v68, 0x3a800000, v0
	v_mul_f32_e32 v69, 0x4b800000, v68
	v_cmp_gt_f32_e32 vcc, s3, v68
	s_nop 1
	v_cndmask_b32_e32 v68, v68, v69, vcc
	v_rsq_f32_e32 v68, v68
	s_nop 0
	v_mul_f32_e32 v69, 0x45800000, v68
	v_cndmask_b32_e32 v68, v68, v69, vcc
	v_pk_mul_f32 v[52:53], v[68:69], v[52:53] op_sel_hi:[0,1]
	v_pk_mul_f32 v[54:55], v[68:69], v[54:55] op_sel_hi:[0,1]
	v_pk_mul_f32 v[52:53], v[20:21], v[52:53]
	v_pk_mul_f32 v[54:55], v[22:23], v[54:55]
	global_store_dwordx4 v[70:71], v[52:55], off offset:-2048
	v_pk_mul_f32 v[56:57], v[68:69], v[56:57] op_sel_hi:[0,1]
	v_pk_mul_f32 v[58:59], v[68:69], v[58:59] op_sel_hi:[0,1]
	v_pk_mul_f32 v[56:57], v[24:25], v[56:57]
	v_pk_mul_f32 v[58:59], v[26:27], v[58:59]
	global_store_dwordx4 v[70:71], v[56:59], off offset:-1024
	v_pk_mul_f32 v[60:61], v[68:69], v[60:61] op_sel_hi:[0,1]
	v_pk_mul_f32 v[62:63], v[68:69], v[62:63] op_sel_hi:[0,1]
	v_pk_mul_f32 v[60:61], v[28:29], v[60:61]
	v_pk_mul_f32 v[62:63], v[30:31], v[62:63]
	global_store_dwordx4 v[70:71], v[60:63], off
	v_pk_mul_f32 v[64:65], v[68:69], v[64:65] op_sel_hi:[0,1]
	v_pk_mul_f32 v[66:67], v[68:69], v[66:67] op_sel_hi:[0,1]
	v_pk_mul_f32 v[64:65], v[32:33], v[64:65]
	v_pk_mul_f32 v[66:67], v[34:35], v[66:67]
	global_store_dwordx4 v[70:71], v[64:67], off offset:1024
	s_branch .Lrn_loop
.Lrn_lastA:
	s_waitcnt vmcnt(0)
	v_fmamk_f32 v18, v18, 0x3a800000, v0
	v_mul_f32_e32 v19, 0x4b800000, v18
	v_cmp_gt_f32_e32 vcc, s3, v18
	s_nop 1
	v_cndmask_b32_e32 v18, v18, v19, vcc
	v_rsq_f32_e32 v18, v18
	s_nop 0
	v_mul_f32_e32 v19, 0x45800000, v18
	v_cndmask_b32_e32 v18, v18, v19, vcc
	v_pk_mul_f32 v[36:37], v[18:19], v[36:37] op_sel_hi:[0,1]
	v_pk_mul_f32 v[38:39], v[18:19], v[38:39] op_sel_hi:[0,1]
	v_pk_mul_f32 v[36:37], v[20:21], v[36:37]
	v_pk_mul_f32 v[38:39], v[22:23], v[38:39]
	global_store_dwordx4 v[4:5], v[36:39], off offset:-2048
	v_pk_mul_f32 v[40:41], v[18:19], v[40:41] op_sel_hi:[0,1]
	v_pk_mul_f32 v[42:43], v[18:19], v[42:43] op_sel_hi:[0,1]
	v_pk_mul_f32 v[40:41], v[24:25], v[40:41]
	v_pk_mul_f32 v[42:43], v[26:27], v[42:43]
	global_store_dwordx4 v[4:5], v[40:43], off offset:-1024
	v_pk_mul_f32 v[44:45], v[18:19], v[44:45] op_sel_hi:[0,1]
	v_pk_mul_f32 v[46:47], v[18:19], v[46:47] op_sel_hi:[0,1]
	v_pk_mul_f32 v[44:45], v[28:29], v[44:45]
	v_pk_mul_f32 v[46:47], v[30:31], v[46:47]
	global_store_dwordx4 v[4:5], v[44:47], off
	v_pk_mul_f32 v[48:49], v[18:19], v[48:49] op_sel_hi:[0,1]
	v_pk_mul_f32 v[50:51], v[18:19], v[50:51] op_sel_hi:[0,1]
	v_pk_mul_f32 v[48:49], v[32:33], v[48:49]
	v_pk_mul_f32 v[50:51], v[34:35], v[50:51]
	global_store_dwordx4 v[4:5], v[48:51], off offset:1024
	s_branch .LBB0_2572
.Lrn_lastB:
	s_waitcnt vmcnt(0)
	v_fmamk_f32 v68, v68, 0x3a800000, v0
	v_mul_f32_e32 v69, 0x4b800000, v68
	v_cmp_gt_f32_e32 vcc, s3, v68
	s_nop 1
	v_cndmask_b32_e32 v68, v68, v69, vcc
	v_rsq_f32_e32 v68, v68
	s_nop 0
	v_mul_f32_e32 v69, 0x45800000, v68
	v_cndmask_b32_e32 v68, v68, v69, vcc
	v_pk_mul_f32 v[52:53], v[68:69], v[52:53] op_sel_hi:[0,1]
	v_pk_mul_f32 v[54:55], v[68:69], v[54:55] op_sel_hi:[0,1]
	v_pk_mul_f32 v[52:53], v[20:21], v[52:53]
	v_pk_mul_f32 v[54:55], v[22:23], v[54:55]
	global_store_dwordx4 v[70:71], v[52:55], off offset:-2048
	v_pk_mul_f32 v[56:57], v[68:69], v[56:57] op_sel_hi:[0,1]
	v_pk_mul_f32 v[58:59], v[68:69], v[58:59] op_sel_hi:[0,1]
	v_pk_mul_f32 v[56:57], v[24:25], v[56:57]
	v_pk_mul_f32 v[58:59], v[26:27], v[58:59]
	global_store_dwordx4 v[70:71], v[56:59], off offset:-1024
	v_pk_mul_f32 v[60:61], v[68:69], v[60:61] op_sel_hi:[0,1]
	v_pk_mul_f32 v[62:63], v[68:69], v[62:63] op_sel_hi:[0,1]
	v_pk_mul_f32 v[60:61], v[28:29], v[60:61]
	v_pk_mul_f32 v[62:63], v[30:31], v[62:63]
	global_store_dwordx4 v[70:71], v[60:63], off
	v_pk_mul_f32 v[64:65], v[68:69], v[64:65] op_sel_hi:[0,1]
	v_pk_mul_f32 v[66:67], v[68:69], v[66:67] op_sel_hi:[0,1]
	v_pk_mul_f32 v[64:65], v[32:33], v[64:65]
	v_pk_mul_f32 v[66:67], v[34:35], v[66:67]
	global_store_dwordx4 v[70:71], v[64:67], off offset:1024
